# P0 weight transposes: row-block order rotated per workgroup so concurrent writes cover all of K (no HBM channel hot spot)
# speedup vs baseline: 1.0151x; 1.0071x over previous
.LBB0_20:
	s_or_b64 exec, exec, s[10:11]
	s_lshl_b32 s17, s97, 14
	s_lshl_b32 s3, s2, 3
	s_add_i32 s3, s97, s3
	s_lshl_b32 s16, s82, 3
	v_readlane_b32 s40, v239, 7
	v_readlane_b32 s41, v239, 8
	v_lshrrev_b32_e32 v120, 5, v182
	v_and_b32_e32 v121, 31, v182
	v_lshlrev_b32_e32 v122, 2, v121
	v_mul_u32_u24_e32 v123, 0x18000, v120
	v_add_u32_e32 v0, v123, v122
	v_add_u32_e32 v1, 0x30000, v0
	v_add_u32_e32 v2, 0x60000, v0
	v_add_u32_e32 v3, 0x90000, v0
	v_add_u32_e32 v4, 0xc0000, v0
	v_add_u32_e32 v5, 0xf0000, v0
	v_add_u32_e32 v6, 0x120000, v0
	v_add_u32_e32 v7, 0x150000, v0
	v_mul_u32_u24_e32 v123, 0x84, v120
	v_add3_u32 v8, v123, v122, s17
	v_and_b32_e32 v124, 7, v182
	v_lshrrev_b32_e32 v125, 3, v182
	v_mul_u32_u24_e32 v123, 0x420, v124
	v_lshlrev_b32_e32 v126, 2, v125
	v_add3_u32 v9, v123, v126, s17
	v_lshlrev_b32_e32 v123, 13, v125
	v_lshl_add_u32 v10, v124, 4, v123
	v_add_u32_e32 v11, 0x10000, v10
	v_add_u32_e32 v12, 0x20000, v10
	v_add_u32_e32 v13, 0x30000, v10
	v_lshlrev_b32_e32 v123, 12, v125
	v_lshl_add_u32 v14, v124, 3, v123
	v_add_u32_e32 v15, 0x8000, v14
	v_add_u32_e32 v16, 0x10000, v14
	v_add_u32_e32 v17, 0x18000, v14
	s_add_u32 s44, s40, 0x10000
	s_addc_u32 s45, s41, 0
	s_mov_b32 s20, s3
	s_cmp_ge_i32 s20, 0x8000
	s_cbranch_scc1 .Lp0a_done
	s_lshr_b32 s37, s20, 9
	s_bfe_u32 s38, s20, 0x40003
	s_lshl_b32 s38, s38, 2
	s_add_i32 s37, s37, s38
	s_and_b32 s37, s37, 63
	s_and_b32 s38, s20, 511
	s_mul_i32 s37, s37, 0x600000
	s_lshl_b32 s38, s38, 7
	s_add_u32 s37, s37, s38
	s_add_u32 s10, s40, s37
	s_addc_u32 s11, s41, 0
	s_add_u32 s12, s10, 0x180000
	s_addc_u32 s13, s11, 0
	s_add_u32 s14, s12, 0x180000
	s_addc_u32 s15, s13, 0
	s_add_u32 s18, s14, 0x180000
	s_addc_u32 s19, s15, 0
	global_load_dword v20, v0, s[10:11] nt
	global_load_dword v21, v1, s[10:11] nt
	global_load_dword v22, v2, s[10:11] nt
	global_load_dword v23, v3, s[10:11] nt
	global_load_dword v24, v4, s[10:11] nt
	global_load_dword v25, v5, s[10:11] nt
	global_load_dword v26, v6, s[10:11] nt
	global_load_dword v27, v7, s[10:11] nt
	global_load_dword v28, v0, s[12:13] nt
	global_load_dword v29, v1, s[12:13] nt
	global_load_dword v30, v2, s[12:13] nt
	global_load_dword v31, v3, s[12:13] nt
	global_load_dword v32, v4, s[12:13] nt
	global_load_dword v33, v5, s[12:13] nt
	global_load_dword v34, v6, s[12:13] nt
	global_load_dword v35, v7, s[12:13] nt
	global_load_dword v36, v0, s[14:15] nt
	global_load_dword v37, v1, s[14:15] nt
	global_load_dword v38, v2, s[14:15] nt
	global_load_dword v39, v3, s[14:15] nt
	global_load_dword v40, v4, s[14:15] nt
	global_load_dword v41, v5, s[14:15] nt
	global_load_dword v42, v6, s[14:15] nt
	global_load_dword v43, v7, s[14:15] nt
	global_load_dword v44, v0, s[18:19] nt
	global_load_dword v45, v1, s[18:19] nt
	global_load_dword v46, v2, s[18:19] nt
	global_load_dword v47, v3, s[18:19] nt
	global_load_dword v48, v4, s[18:19] nt
	global_load_dword v49, v5, s[18:19] nt
	global_load_dword v50, v6, s[18:19] nt
	global_load_dword v51, v7, s[18:19] nt
	s_mov_b32 s36, s20
	s_add_i32 s20, s20, s16
.Lp0a_loop:
	s_cmp_ge_i32 s20, 0x8000
	s_cbranch_scc1 .Lp0a_lastA
	s_lshr_b32 s37, s20, 9
	s_bfe_u32 s38, s20, 0x40003
	s_lshl_b32 s38, s38, 2
	s_add_i32 s37, s37, s38
	s_and_b32 s37, s37, 63
	s_and_b32 s38, s20, 511
	s_mul_i32 s37, s37, 0x600000
	s_lshl_b32 s38, s38, 7
	s_add_u32 s37, s37, s38
	s_add_u32 s10, s40, s37
	s_addc_u32 s11, s41, 0
	s_add_u32 s12, s10, 0x180000
	s_addc_u32 s13, s11, 0
	s_add_u32 s14, s12, 0x180000
	s_addc_u32 s15, s13, 0
	s_add_u32 s18, s14, 0x180000
	s_addc_u32 s19, s15, 0
	global_load_dword v52, v0, s[10:11] nt
	global_load_dword v53, v1, s[10:11] nt
	global_load_dword v54, v2, s[10:11] nt
	global_load_dword v55, v3, s[10:11] nt
	global_load_dword v56, v4, s[10:11] nt
	global_load_dword v57, v5, s[10:11] nt
	global_load_dword v58, v6, s[10:11] nt
	global_load_dword v59, v7, s[10:11] nt
	global_load_dword v60, v0, s[12:13] nt
	global_load_dword v61, v1, s[12:13] nt
	global_load_dword v62, v2, s[12:13] nt
	global_load_dword v63, v3, s[12:13] nt
	global_load_dword v64, v4, s[12:13] nt
	global_load_dword v65, v5, s[12:13] nt
	global_load_dword v66, v6, s[12:13] nt
	global_load_dword v67, v7, s[12:13] nt
	global_load_dword v68, v0, s[14:15] nt
	global_load_dword v69, v1, s[14:15] nt
	global_load_dword v70, v2, s[14:15] nt
	global_load_dword v71, v3, s[14:15] nt
	global_load_dword v72, v4, s[14:15] nt
	global_load_dword v73, v5, s[14:15] nt
	global_load_dword v74, v6, s[14:15] nt
	global_load_dword v75, v7, s[14:15] nt
	global_load_dword v76, v0, s[18:19] nt
	global_load_dword v77, v1, s[18:19] nt
	global_load_dword v78, v2, s[18:19] nt
	global_load_dword v79, v3, s[18:19] nt
	global_load_dword v80, v4, s[18:19] nt
	global_load_dword v81, v5, s[18:19] nt
	global_load_dword v82, v6, s[18:19] nt
	global_load_dword v83, v7, s[18:19] nt
	s_waitcnt vmcnt(32)
	ds_write_b32 v8, v20 offset:0
	ds_write_b32 v8, v21 offset:264
	ds_write_b32 v8, v22 offset:528
	ds_write_b32 v8, v23 offset:792
	ds_write_b32 v8, v24 offset:1056
	ds_write_b32 v8, v25 offset:1320
	ds_write_b32 v8, v26 offset:1584
	ds_write_b32 v8, v27 offset:1848
	ds_write_b32 v8, v28 offset:2112
	ds_write_b32 v8, v29 offset:2376
	ds_write_b32 v8, v30 offset:2640
	ds_write_b32 v8, v31 offset:2904
	ds_write_b32 v8, v32 offset:3168
	ds_write_b32 v8, v33 offset:3432
	ds_write_b32 v8, v34 offset:3696
	ds_write_b32 v8, v35 offset:3960
	ds_write_b32 v8, v36 offset:4224
	ds_write_b32 v8, v37 offset:4488
	ds_write_b32 v8, v38 offset:4752
	ds_write_b32 v8, v39 offset:5016
	ds_write_b32 v8, v40 offset:5280
	ds_write_b32 v8, v41 offset:5544
	ds_write_b32 v8, v42 offset:5808
	ds_write_b32 v8, v43 offset:6072
	ds_write_b32 v8, v44 offset:6336
	ds_write_b32 v8, v45 offset:6600
	ds_write_b32 v8, v46 offset:6864
	ds_write_b32 v8, v47 offset:7128
	ds_write_b32 v8, v48 offset:7392
	ds_write_b32 v8, v49 offset:7656
	ds_write_b32 v8, v50 offset:7920
	ds_write_b32 v8, v51 offset:8184
	s_lshr_b32 s37, s36, 9
	s_bfe_u32 s38, s36, 0x40003
	s_lshl_b32 s38, s38, 2
	s_add_i32 s37, s37, s38
	s_and_b32 s37, s37, 63
	s_and_b32 s38, s36, 511
	s_lshl_b32 s37, s37, 7
	s_lshl_b32 s38, s38, 18
	s_add_u32 s37, s37, s38
	s_add_u32 s46, s8, s37
	s_addc_u32 s47, s9, 0
	s_waitcnt lgkmcnt(0)
	ds_read2_b32 v[84:85], v9 offset0:0 offset1:8
	ds_read2_b32 v[86:87], v9 offset0:33 offset1:41
	ds_read2_b32 v[88:89], v9 offset0:66 offset1:74
	ds_read2_b32 v[90:91], v9 offset0:99 offset1:107
	ds_read2_b32 v[92:93], v9 offset0:132 offset1:140
	ds_read2_b32 v[94:95], v9 offset0:165 offset1:173
	ds_read2_b32 v[96:97], v9 offset0:198 offset1:206
	ds_read2_b32 v[98:99], v9 offset0:231 offset1:239
	ds_read2_b32 v[100:101], v9 offset0:16 offset1:24
	ds_read2_b32 v[102:103], v9 offset0:49 offset1:57
	ds_read2_b32 v[104:105], v9 offset0:82 offset1:90
	ds_read2_b32 v[106:107], v9 offset0:115 offset1:123
	ds_read2_b32 v[108:109], v9 offset0:148 offset1:156
	ds_read2_b32 v[110:111], v9 offset0:181 offset1:189
	ds_read2_b32 v[112:113], v9 offset0:214 offset1:222
	ds_read2_b32 v[114:115], v9 offset0:247 offset1:255
	s_waitcnt lgkmcnt(8)
	v_cvt_pk_bf16_f32 v116, v84, v86
	v_cvt_pk_bf16_f32 v117, v88, v90
	v_cvt_pk_bf16_f32 v118, v92, v94
	v_cvt_pk_bf16_f32 v119, v96, v98
	global_store_dwordx4 v10, v[116:119], s[46:47]
	v_cvt_pk_bf16_f32 v120, v85, v87
	v_cvt_pk_bf16_f32 v121, v89, v91
	v_cvt_pk_bf16_f32 v122, v93, v95
	v_cvt_pk_bf16_f32 v123, v97, v99
	global_store_dwordx4 v11, v[120:123], s[46:47]
	s_waitcnt lgkmcnt(0)
	v_cvt_pk_bf16_f32 v124, v100, v102
	v_cvt_pk_bf16_f32 v125, v104, v106
	v_cvt_pk_bf16_f32 v126, v108, v110
	v_cvt_pk_bf16_f32 v127, v112, v114
	global_store_dwordx4 v12, v[124:127], s[46:47]
	v_cvt_pk_bf16_f32 v128, v101, v103
	v_cvt_pk_bf16_f32 v129, v105, v107
	v_cvt_pk_bf16_f32 v130, v109, v111
	v_cvt_pk_bf16_f32 v131, v113, v115
	global_store_dwordx4 v13, v[128:131], s[46:47]
	s_mov_b32 s36, s20
	s_add_i32 s20, s20, s16
	s_cmp_ge_i32 s20, 0x8000
	s_cbranch_scc1 .Lp0a_lastB
	s_lshr_b32 s37, s20, 9
	s_bfe_u32 s38, s20, 0x40003
	s_lshl_b32 s38, s38, 2
	s_add_i32 s37, s37, s38
	s_and_b32 s37, s37, 63
	s_and_b32 s38, s20, 511
	s_mul_i32 s37, s37, 0x600000
	s_lshl_b32 s38, s38, 7
	s_add_u32 s37, s37, s38
	s_add_u32 s10, s40, s37
	s_addc_u32 s11, s41, 0
	s_add_u32 s12, s10, 0x180000
	s_addc_u32 s13, s11, 0
	s_add_u32 s14, s12, 0x180000
	s_addc_u32 s15, s13, 0
	s_add_u32 s18, s14, 0x180000
	s_addc_u32 s19, s15, 0
	global_load_dword v20, v0, s[10:11] nt
	global_load_dword v21, v1, s[10:11] nt
	global_load_dword v22, v2, s[10:11] nt
	global_load_dword v23, v3, s[10:11] nt
	global_load_dword v24, v4, s[10:11] nt
	global_load_dword v25, v5, s[10:11] nt
	global_load_dword v26, v6, s[10:11] nt
	global_load_dword v27, v7, s[10:11] nt
	global_load_dword v28, v0, s[12:13] nt
	global_load_dword v29, v1, s[12:13] nt
	global_load_dword v30, v2, s[12:13] nt
	global_load_dword v31, v3, s[12:13] nt
	global_load_dword v32, v4, s[12:13] nt
	global_load_dword v33, v5, s[12:13] nt
	global_load_dword v34, v6, s[12:13] nt
	global_load_dword v35, v7, s[12:13] nt
	global_load_dword v36, v0, s[14:15] nt
	global_load_dword v37, v1, s[14:15] nt
	global_load_dword v38, v2, s[14:15] nt
	global_load_dword v39, v3, s[14:15] nt
	global_load_dword v40, v4, s[14:15] nt
	global_load_dword v41, v5, s[14:15] nt
	global_load_dword v42, v6, s[14:15] nt
	global_load_dword v43, v7, s[14:15] nt
	global_load_dword v44, v0, s[18:19] nt
	global_load_dword v45, v1, s[18:19] nt
	global_load_dword v46, v2, s[18:19] nt
	global_load_dword v47, v3, s[18:19] nt
	global_load_dword v48, v4, s[18:19] nt
	global_load_dword v49, v5, s[18:19] nt
	global_load_dword v50, v6, s[18:19] nt
	global_load_dword v51, v7, s[18:19] nt
	s_waitcnt vmcnt(32)
	ds_write_b32 v8, v52 offset:0
	ds_write_b32 v8, v53 offset:264
	ds_write_b32 v8, v54 offset:528
	ds_write_b32 v8, v55 offset:792
	ds_write_b32 v8, v56 offset:1056
	ds_write_b32 v8, v57 offset:1320
	ds_write_b32 v8, v58 offset:1584
	ds_write_b32 v8, v59 offset:1848
	ds_write_b32 v8, v60 offset:2112
	ds_write_b32 v8, v61 offset:2376
	ds_write_b32 v8, v62 offset:2640
	ds_write_b32 v8, v63 offset:2904
	ds_write_b32 v8, v64 offset:3168
	ds_write_b32 v8, v65 offset:3432
	ds_write_b32 v8, v66 offset:3696
	ds_write_b32 v8, v67 offset:3960
	ds_write_b32 v8, v68 offset:4224
	ds_write_b32 v8, v69 offset:4488
	ds_write_b32 v8, v70 offset:4752
	ds_write_b32 v8, v71 offset:5016
	ds_write_b32 v8, v72 offset:5280
	ds_write_b32 v8, v73 offset:5544
	ds_write_b32 v8, v74 offset:5808
	ds_write_b32 v8, v75 offset:6072
	ds_write_b32 v8, v76 offset:6336
	ds_write_b32 v8, v77 offset:6600
	ds_write_b32 v8, v78 offset:6864
	ds_write_b32 v8, v79 offset:7128
	ds_write_b32 v8, v80 offset:7392
	ds_write_b32 v8, v81 offset:7656
	ds_write_b32 v8, v82 offset:7920
	ds_write_b32 v8, v83 offset:8184
	s_lshr_b32 s37, s36, 9
	s_bfe_u32 s38, s36, 0x40003
	s_lshl_b32 s38, s38, 2
	s_add_i32 s37, s37, s38
	s_and_b32 s37, s37, 63
	s_and_b32 s38, s36, 511
	s_lshl_b32 s37, s37, 7
	s_lshl_b32 s38, s38, 18
	s_add_u32 s37, s37, s38
	s_add_u32 s46, s8, s37
	s_addc_u32 s47, s9, 0
	s_waitcnt lgkmcnt(0)
	ds_read2_b32 v[84:85], v9 offset0:0 offset1:8
	ds_read2_b32 v[86:87], v9 offset0:33 offset1:41
	ds_read2_b32 v[88:89], v9 offset0:66 offset1:74
	ds_read2_b32 v[90:91], v9 offset0:99 offset1:107
	ds_read2_b32 v[92:93], v9 offset0:132 offset1:140
	ds_read2_b32 v[94:95], v9 offset0:165 offset1:173
	ds_read2_b32 v[96:97], v9 offset0:198 offset1:206
	ds_read2_b32 v[98:99], v9 offset0:231 offset1:239
	ds_read2_b32 v[100:101], v9 offset0:16 offset1:24
	ds_read2_b32 v[102:103], v9 offset0:49 offset1:57
	ds_read2_b32 v[104:105], v9 offset0:82 offset1:90
	ds_read2_b32 v[106:107], v9 offset0:115 offset1:123
	ds_read2_b32 v[108:109], v9 offset0:148 offset1:156
	ds_read2_b32 v[110:111], v9 offset0:181 offset1:189
	ds_read2_b32 v[112:113], v9 offset0:214 offset1:222
	ds_read2_b32 v[114:115], v9 offset0:247 offset1:255
	s_waitcnt lgkmcnt(8)
	v_cvt_pk_bf16_f32 v116, v84, v86
	v_cvt_pk_bf16_f32 v117, v88, v90
	v_cvt_pk_bf16_f32 v118, v92, v94
	v_cvt_pk_bf16_f32 v119, v96, v98
	global_store_dwordx4 v10, v[116:119], s[46:47]
	v_cvt_pk_bf16_f32 v120, v85, v87
	v_cvt_pk_bf16_f32 v121, v89, v91
	v_cvt_pk_bf16_f32 v122, v93, v95
	v_cvt_pk_bf16_f32 v123, v97, v99
	global_store_dwordx4 v11, v[120:123], s[46:47]
	s_waitcnt lgkmcnt(0)
	v_cvt_pk_bf16_f32 v124, v100, v102
	v_cvt_pk_bf16_f32 v125, v104, v106
	v_cvt_pk_bf16_f32 v126, v108, v110
	v_cvt_pk_bf16_f32 v127, v112, v114
	global_store_dwordx4 v12, v[124:127], s[46:47]
	v_cvt_pk_bf16_f32 v128, v101, v103
	v_cvt_pk_bf16_f32 v129, v105, v107
	v_cvt_pk_bf16_f32 v130, v109, v111
	v_cvt_pk_bf16_f32 v131, v113, v115
	global_store_dwordx4 v13, v[128:131], s[46:47]
	s_mov_b32 s36, s20
	s_add_i32 s20, s20, s16
	s_branch .Lp0a_loop
.Lp0a_lastA:
	s_waitcnt vmcnt(0)
	ds_write_b32 v8, v20 offset:0
	ds_write_b32 v8, v21 offset:264
	ds_write_b32 v8, v22 offset:528
	ds_write_b32 v8, v23 offset:792
	ds_write_b32 v8, v24 offset:1056
	ds_write_b32 v8, v25 offset:1320
	ds_write_b32 v8, v26 offset:1584
	ds_write_b32 v8, v27 offset:1848
	ds_write_b32 v8, v28 offset:2112
	ds_write_b32 v8, v29 offset:2376
	ds_write_b32 v8, v30 offset:2640
	ds_write_b32 v8, v31 offset:2904
	ds_write_b32 v8, v32 offset:3168
	ds_write_b32 v8, v33 offset:3432
	ds_write_b32 v8, v34 offset:3696
	ds_write_b32 v8, v35 offset:3960
	ds_write_b32 v8, v36 offset:4224
	ds_write_b32 v8, v37 offset:4488
	ds_write_b32 v8, v38 offset:4752
	ds_write_b32 v8, v39 offset:5016
	ds_write_b32 v8, v40 offset:5280
	ds_write_b32 v8, v41 offset:5544
	ds_write_b32 v8, v42 offset:5808
	ds_write_b32 v8, v43 offset:6072
	ds_write_b32 v8, v44 offset:6336
	ds_write_b32 v8, v45 offset:6600
	ds_write_b32 v8, v46 offset:6864
	ds_write_b32 v8, v47 offset:7128
	ds_write_b32 v8, v48 offset:7392
	ds_write_b32 v8, v49 offset:7656
	ds_write_b32 v8, v50 offset:7920
	ds_write_b32 v8, v51 offset:8184
	s_lshr_b32 s37, s36, 9
	s_bfe_u32 s38, s36, 0x40003
	s_lshl_b32 s38, s38, 2
	s_add_i32 s37, s37, s38
	s_and_b32 s37, s37, 63
	s_and_b32 s38, s36, 511
	s_lshl_b32 s37, s37, 7
	s_lshl_b32 s38, s38, 18
	s_add_u32 s37, s37, s38
	s_add_u32 s46, s8, s37
	s_addc_u32 s47, s9, 0
	s_waitcnt lgkmcnt(0)
	ds_read2_b32 v[84:85], v9 offset0:0 offset1:8
	ds_read2_b32 v[86:87], v9 offset0:33 offset1:41
	ds_read2_b32 v[88:89], v9 offset0:66 offset1:74
	ds_read2_b32 v[90:91], v9 offset0:99 offset1:107
	ds_read2_b32 v[92:93], v9 offset0:132 offset1:140
	ds_read2_b32 v[94:95], v9 offset0:165 offset1:173
	ds_read2_b32 v[96:97], v9 offset0:198 offset1:206
	ds_read2_b32 v[98:99], v9 offset0:231 offset1:239
	ds_read2_b32 v[100:101], v9 offset0:16 offset1:24
	ds_read2_b32 v[102:103], v9 offset0:49 offset1:57
	ds_read2_b32 v[104:105], v9 offset0:82 offset1:90
	ds_read2_b32 v[106:107], v9 offset0:115 offset1:123
	ds_read2_b32 v[108:109], v9 offset0:148 offset1:156
	ds_read2_b32 v[110:111], v9 offset0:181 offset1:189
	ds_read2_b32 v[112:113], v9 offset0:214 offset1:222
	ds_read2_b32 v[114:115], v9 offset0:247 offset1:255
	s_waitcnt lgkmcnt(8)
	v_cvt_pk_bf16_f32 v116, v84, v86
	v_cvt_pk_bf16_f32 v117, v88, v90
	v_cvt_pk_bf16_f32 v118, v92, v94
	v_cvt_pk_bf16_f32 v119, v96, v98
	global_store_dwordx4 v10, v[116:119], s[46:47]
	v_cvt_pk_bf16_f32 v120, v85, v87
	v_cvt_pk_bf16_f32 v121, v89, v91
	v_cvt_pk_bf16_f32 v122, v93, v95
	v_cvt_pk_bf16_f32 v123, v97, v99
	global_store_dwordx4 v11, v[120:123], s[46:47]
	s_waitcnt lgkmcnt(0)
	v_cvt_pk_bf16_f32 v124, v100, v102
	v_cvt_pk_bf16_f32 v125, v104, v106
	v_cvt_pk_bf16_f32 v126, v108, v110
	v_cvt_pk_bf16_f32 v127, v112, v114
	global_store_dwordx4 v12, v[124:127], s[46:47]
	v_cvt_pk_bf16_f32 v128, v101, v103
	v_cvt_pk_bf16_f32 v129, v105, v107
	v_cvt_pk_bf16_f32 v130, v109, v111
	v_cvt_pk_bf16_f32 v131, v113, v115
	global_store_dwordx4 v13, v[128:131], s[46:47]
	s_branch .Lp0a_done
.Lp0a_lastB:
	s_waitcnt vmcnt(0)
	ds_write_b32 v8, v52 offset:0
	ds_write_b32 v8, v53 offset:264
	ds_write_b32 v8, v54 offset:528
	ds_write_b32 v8, v55 offset:792
	ds_write_b32 v8, v56 offset:1056
	ds_write_b32 v8, v57 offset:1320
	ds_write_b32 v8, v58 offset:1584
	ds_write_b32 v8, v59 offset:1848
	ds_write_b32 v8, v60 offset:2112
	ds_write_b32 v8, v61 offset:2376
	ds_write_b32 v8, v62 offset:2640
	ds_write_b32 v8, v63 offset:2904
	ds_write_b32 v8, v64 offset:3168
	ds_write_b32 v8, v65 offset:3432
	ds_write_b32 v8, v66 offset:3696
	ds_write_b32 v8, v67 offset:3960
	ds_write_b32 v8, v68 offset:4224
	ds_write_b32 v8, v69 offset:4488
	ds_write_b32 v8, v70 offset:4752
	ds_write_b32 v8, v71 offset:5016
	ds_write_b32 v8, v72 offset:5280
	ds_write_b32 v8, v73 offset:5544
	ds_write_b32 v8, v74 offset:5808
	ds_write_b32 v8, v75 offset:6072
	ds_write_b32 v8, v76 offset:6336
	ds_write_b32 v8, v77 offset:6600
	ds_write_b32 v8, v78 offset:6864
	ds_write_b32 v8, v79 offset:7128
	ds_write_b32 v8, v80 offset:7392
	ds_write_b32 v8, v81 offset:7656
	ds_write_b32 v8, v82 offset:7920
	ds_write_b32 v8, v83 offset:8184
	s_lshr_b32 s37, s36, 9
	s_bfe_u32 s38, s36, 0x40003
	s_lshl_b32 s38, s38, 2
	s_add_i32 s37, s37, s38
	s_and_b32 s37, s37, 63
	s_and_b32 s38, s36, 511
	s_lshl_b32 s37, s37, 7
	s_lshl_b32 s38, s38, 18
	s_add_u32 s37, s37, s38
	s_add_u32 s46, s8, s37
	s_addc_u32 s47, s9, 0
	s_waitcnt lgkmcnt(0)
	ds_read2_b32 v[84:85], v9 offset0:0 offset1:8
	ds_read2_b32 v[86:87], v9 offset0:33 offset1:41
	ds_read2_b32 v[88:89], v9 offset0:66 offset1:74
	ds_read2_b32 v[90:91], v9 offset0:99 offset1:107
	ds_read2_b32 v[92:93], v9 offset0:132 offset1:140
	ds_read2_b32 v[94:95], v9 offset0:165 offset1:173
	ds_read2_b32 v[96:97], v9 offset0:198 offset1:206
	ds_read2_b32 v[98:99], v9 offset0:231 offset1:239
	ds_read2_b32 v[100:101], v9 offset0:16 offset1:24
	ds_read2_b32 v[102:103], v9 offset0:49 offset1:57
	ds_read2_b32 v[104:105], v9 offset0:82 offset1:90
	ds_read2_b32 v[106:107], v9 offset0:115 offset1:123
	ds_read2_b32 v[108:109], v9 offset0:148 offset1:156
	ds_read2_b32 v[110:111], v9 offset0:181 offset1:189
	ds_read2_b32 v[112:113], v9 offset0:214 offset1:222
	ds_read2_b32 v[114:115], v9 offset0:247 offset1:255
	s_waitcnt lgkmcnt(8)
	v_cvt_pk_bf16_f32 v116, v84, v86
	v_cvt_pk_bf16_f32 v117, v88, v90
	v_cvt_pk_bf16_f32 v118, v92, v94
	v_cvt_pk_bf16_f32 v119, v96, v98
	global_store_dwordx4 v10, v[116:119], s[46:47]
	v_cvt_pk_bf16_f32 v120, v85, v87
	v_cvt_pk_bf16_f32 v121, v89, v91
	v_cvt_pk_bf16_f32 v122, v93, v95
	v_cvt_pk_bf16_f32 v123, v97, v99
	global_store_dwordx4 v11, v[120:123], s[46:47]
	s_waitcnt lgkmcnt(0)
	v_cvt_pk_bf16_f32 v124, v100, v102
	v_cvt_pk_bf16_f32 v125, v104, v106
	v_cvt_pk_bf16_f32 v126, v108, v110
	v_cvt_pk_bf16_f32 v127, v112, v114
	global_store_dwordx4 v12, v[124:127], s[46:47]
	v_cvt_pk_bf16_f32 v128, v101, v103
	v_cvt_pk_bf16_f32 v129, v105, v107
	v_cvt_pk_bf16_f32 v130, v109, v111
	v_cvt_pk_bf16_f32 v131, v113, v115
	global_store_dwordx4 v13, v[128:131], s[46:47]
.Lp0a_done:
	s_mov_b32 s20, s3
	s_cmp_ge_i32 s20, 0x4000
	s_cbranch_scc1 .Lp0b_done
	s_lshr_b32 s37, s20, 8
	s_bfe_u32 s38, s20, 0x40003
	s_lshl_b32 s38, s38, 2
	s_add_i32 s37, s37, s38
	s_and_b32 s37, s37, 63
	s_and_b32 s38, s20, 255
	s_mul_i32 s37, s37, 0x600000
	s_lshl_b32 s38, s38, 7
	s_add_u32 s37, s37, s38
	s_add_u32 s10, s44, s37
	s_addc_u32 s11, s45, 0
	s_add_u32 s12, s10, 0x180000
	s_addc_u32 s13, s11, 0
	s_add_u32 s14, s12, 0x180000
	s_addc_u32 s15, s13, 0
	s_add_u32 s18, s14, 0x180000
	s_addc_u32 s19, s15, 0
	global_load_dword v20, v0, s[10:11] nt
	global_load_dword v21, v1, s[10:11] nt
	global_load_dword v22, v2, s[10:11] nt
	global_load_dword v23, v3, s[10:11] nt
	global_load_dword v24, v4, s[10:11] nt
	global_load_dword v25, v5, s[10:11] nt
	global_load_dword v26, v6, s[10:11] nt
	global_load_dword v27, v7, s[10:11] nt
	global_load_dword v28, v0, s[12:13] nt
	global_load_dword v29, v1, s[12:13] nt
	global_load_dword v30, v2, s[12:13] nt
	global_load_dword v31, v3, s[12:13] nt
	global_load_dword v32, v4, s[12:13] nt
	global_load_dword v33, v5, s[12:13] nt
	global_load_dword v34, v6, s[12:13] nt
	global_load_dword v35, v7, s[12:13] nt
	global_load_dword v36, v0, s[14:15] nt
	global_load_dword v37, v1, s[14:15] nt
	global_load_dword v38, v2, s[14:15] nt
	global_load_dword v39, v3, s[14:15] nt
	global_load_dword v40, v4, s[14:15] nt
	global_load_dword v41, v5, s[14:15] nt
	global_load_dword v42, v6, s[14:15] nt
	global_load_dword v43, v7, s[14:15] nt
	global_load_dword v44, v0, s[18:19] nt
	global_load_dword v45, v1, s[18:19] nt
	global_load_dword v46, v2, s[18:19] nt
	global_load_dword v47, v3, s[18:19] nt
	global_load_dword v48, v4, s[18:19] nt
	global_load_dword v49, v5, s[18:19] nt
	global_load_dword v50, v6, s[18:19] nt
	global_load_dword v51, v7, s[18:19] nt
	s_mov_b32 s36, s20
	s_add_i32 s20, s20, s16
.Lp0b_loop:
	s_cmp_ge_i32 s20, 0x4000
	s_cbranch_scc1 .Lp0b_lastA
	s_lshr_b32 s37, s20, 8
	s_bfe_u32 s38, s20, 0x40003
	s_lshl_b32 s38, s38, 2
	s_add_i32 s37, s37, s38
	s_and_b32 s37, s37, 63
	s_and_b32 s38, s20, 255
	s_mul_i32 s37, s37, 0x600000
	s_lshl_b32 s38, s38, 7
	s_add_u32 s37, s37, s38
	s_add_u32 s10, s44, s37
	s_addc_u32 s11, s45, 0
	s_add_u32 s12, s10, 0x180000
	s_addc_u32 s13, s11, 0
	s_add_u32 s14, s12, 0x180000
	s_addc_u32 s15, s13, 0
	s_add_u32 s18, s14, 0x180000
	s_addc_u32 s19, s15, 0
	global_load_dword v52, v0, s[10:11] nt
	global_load_dword v53, v1, s[10:11] nt
	global_load_dword v54, v2, s[10:11] nt
	global_load_dword v55, v3, s[10:11] nt
	global_load_dword v56, v4, s[10:11] nt
	global_load_dword v57, v5, s[10:11] nt
	global_load_dword v58, v6, s[10:11] nt
	global_load_dword v59, v7, s[10:11] nt
	global_load_dword v60, v0, s[12:13] nt
	global_load_dword v61, v1, s[12:13] nt
	global_load_dword v62, v2, s[12:13] nt
	global_load_dword v63, v3, s[12:13] nt
	global_load_dword v64, v4, s[12:13] nt
	global_load_dword v65, v5, s[12:13] nt
	global_load_dword v66, v6, s[12:13] nt
	global_load_dword v67, v7, s[12:13] nt
	global_load_dword v68, v0, s[14:15] nt
	global_load_dword v69, v1, s[14:15] nt
	global_load_dword v70, v2, s[14:15] nt
	global_load_dword v71, v3, s[14:15] nt
	global_load_dword v72, v4, s[14:15] nt
	global_load_dword v73, v5, s[14:15] nt
	global_load_dword v74, v6, s[14:15] nt
	global_load_dword v75, v7, s[14:15] nt
	global_load_dword v76, v0, s[18:19] nt
	global_load_dword v77, v1, s[18:19] nt
	global_load_dword v78, v2, s[18:19] nt
	global_load_dword v79, v3, s[18:19] nt
	global_load_dword v80, v4, s[18:19] nt
	global_load_dword v81, v5, s[18:19] nt
	global_load_dword v82, v6, s[18:19] nt
	global_load_dword v83, v7, s[18:19] nt
	s_waitcnt vmcnt(32)
	ds_write_b32 v8, v20 offset:0
	ds_write_b32 v8, v21 offset:264
	ds_write_b32 v8, v22 offset:528
	ds_write_b32 v8, v23 offset:792
	ds_write_b32 v8, v24 offset:1056
	ds_write_b32 v8, v25 offset:1320
	ds_write_b32 v8, v26 offset:1584
	ds_write_b32 v8, v27 offset:1848
	ds_write_b32 v8, v28 offset:2112
	ds_write_b32 v8, v29 offset:2376
	ds_write_b32 v8, v30 offset:2640
	ds_write_b32 v8, v31 offset:2904
	ds_write_b32 v8, v32 offset:3168
	ds_write_b32 v8, v33 offset:3432
	ds_write_b32 v8, v34 offset:3696
	ds_write_b32 v8, v35 offset:3960
	ds_write_b32 v8, v36 offset:4224
	ds_write_b32 v8, v37 offset:4488
	ds_write_b32 v8, v38 offset:4752
	ds_write_b32 v8, v39 offset:5016
	ds_write_b32 v8, v40 offset:5280
	ds_write_b32 v8, v41 offset:5544
	ds_write_b32 v8, v42 offset:5808
	ds_write_b32 v8, v43 offset:6072
	ds_write_b32 v8, v44 offset:6336
	ds_write_b32 v8, v45 offset:6600
	ds_write_b32 v8, v46 offset:6864
	ds_write_b32 v8, v47 offset:7128
	ds_write_b32 v8, v48 offset:7392
	ds_write_b32 v8, v49 offset:7656
	ds_write_b32 v8, v50 offset:7920
	ds_write_b32 v8, v51 offset:8184
	s_lshr_b32 s37, s36, 8
	s_bfe_u32 s38, s36, 0x40003
	s_lshl_b32 s38, s38, 2
	s_add_i32 s37, s37, s38
	s_and_b32 s37, s37, 63
	s_and_b32 s38, s36, 255
	s_lshl_b32 s37, s37, 6
	s_lshl_b32 s38, s38, 17
	s_add_u32 s37, s37, s38
	s_add_u32 s46, s0, s37
	s_addc_u32 s47, s1, 0
	s_waitcnt lgkmcnt(0)
	ds_read2_b32 v[84:85], v9 offset0:0 offset1:8
	ds_read2_b32 v[86:87], v9 offset0:33 offset1:41
	ds_read2_b32 v[88:89], v9 offset0:66 offset1:74
	ds_read2_b32 v[90:91], v9 offset0:99 offset1:107
	ds_read2_b32 v[92:93], v9 offset0:132 offset1:140
	ds_read2_b32 v[94:95], v9 offset0:165 offset1:173
	ds_read2_b32 v[96:97], v9 offset0:198 offset1:206
	ds_read2_b32 v[98:99], v9 offset0:231 offset1:239
	ds_read2_b32 v[100:101], v9 offset0:16 offset1:24
	ds_read2_b32 v[102:103], v9 offset0:49 offset1:57
	ds_read2_b32 v[104:105], v9 offset0:82 offset1:90
	ds_read2_b32 v[106:107], v9 offset0:115 offset1:123
	ds_read2_b32 v[108:109], v9 offset0:148 offset1:156
	ds_read2_b32 v[110:111], v9 offset0:181 offset1:189
	ds_read2_b32 v[112:113], v9 offset0:214 offset1:222
	ds_read2_b32 v[114:115], v9 offset0:247 offset1:255
	s_waitcnt lgkmcnt(0)
	v_mul_f32_e32 v84, 0x42800000, v84
	v_mul_f32_e32 v85, 0x42800000, v85
	v_mul_f32_e32 v86, 0x42800000, v86
	v_mul_f32_e32 v87, 0x42800000, v87
	v_mul_f32_e32 v88, 0x42800000, v88
	v_mul_f32_e32 v89, 0x42800000, v89
	v_mul_f32_e32 v90, 0x42800000, v90
	v_mul_f32_e32 v91, 0x42800000, v91
	v_mul_f32_e32 v92, 0x42800000, v92
	v_mul_f32_e32 v93, 0x42800000, v93
	v_mul_f32_e32 v94, 0x42800000, v94
	v_mul_f32_e32 v95, 0x42800000, v95
	v_mul_f32_e32 v96, 0x42800000, v96
	v_mul_f32_e32 v97, 0x42800000, v97
	v_mul_f32_e32 v98, 0x42800000, v98
	v_mul_f32_e32 v99, 0x42800000, v99
	v_mul_f32_e32 v100, 0x42800000, v100
	v_mul_f32_e32 v101, 0x42800000, v101
	v_mul_f32_e32 v102, 0x42800000, v102
	v_mul_f32_e32 v103, 0x42800000, v103
	v_mul_f32_e32 v104, 0x42800000, v104
	v_mul_f32_e32 v105, 0x42800000, v105
	v_mul_f32_e32 v106, 0x42800000, v106
	v_mul_f32_e32 v107, 0x42800000, v107
	v_mul_f32_e32 v108, 0x42800000, v108
	v_mul_f32_e32 v109, 0x42800000, v109
	v_mul_f32_e32 v110, 0x42800000, v110
	v_mul_f32_e32 v111, 0x42800000, v111
	v_mul_f32_e32 v112, 0x42800000, v112
	v_mul_f32_e32 v113, 0x42800000, v113
	v_mul_f32_e32 v114, 0x42800000, v114
	v_mul_f32_e32 v115, 0x42800000, v115
	v_cvt_pk_fp8_f32 v116, v84, v86
	v_cvt_pk_fp8_f32 v117, v92, v94
	v_cvt_pk_fp8_f32 v116, v88, v90 op_sel:[0,0,1]
	v_cvt_pk_fp8_f32 v117, v96, v98 op_sel:[0,0,1]
	v_cvt_pk_fp8_f32 v118, v85, v87
	v_cvt_pk_fp8_f32 v119, v93, v95
	v_cvt_pk_fp8_f32 v118, v89, v91 op_sel:[0,0,1]
	v_cvt_pk_fp8_f32 v119, v97, v99 op_sel:[0,0,1]
	v_cvt_pk_fp8_f32 v120, v100, v102
	v_cvt_pk_fp8_f32 v121, v108, v110
	v_cvt_pk_fp8_f32 v120, v104, v106 op_sel:[0,0,1]
	v_cvt_pk_fp8_f32 v121, v112, v114 op_sel:[0,0,1]
	v_cvt_pk_fp8_f32 v122, v101, v103
	v_cvt_pk_fp8_f32 v123, v109, v111
	v_cvt_pk_fp8_f32 v122, v105, v107 op_sel:[0,0,1]
	v_cvt_pk_fp8_f32 v123, v113, v115 op_sel:[0,0,1]
	global_store_dwordx2 v14, v[116:117], s[46:47]
	global_store_dwordx2 v15, v[118:119], s[46:47]
	global_store_dwordx2 v16, v[120:121], s[46:47]
	global_store_dwordx2 v17, v[122:123], s[46:47]
	s_mov_b32 s36, s20
	s_add_i32 s20, s20, s16
	s_cmp_ge_i32 s20, 0x4000
	s_cbranch_scc1 .Lp0b_lastB
	s_lshr_b32 s37, s20, 8
	s_bfe_u32 s38, s20, 0x40003
	s_lshl_b32 s38, s38, 2
	s_add_i32 s37, s37, s38
	s_and_b32 s37, s37, 63
	s_and_b32 s38, s20, 255
	s_mul_i32 s37, s37, 0x600000
	s_lshl_b32 s38, s38, 7
	s_add_u32 s37, s37, s38
	s_add_u32 s10, s44, s37
	s_addc_u32 s11, s45, 0
	s_add_u32 s12, s10, 0x180000
	s_addc_u32 s13, s11, 0
	s_add_u32 s14, s12, 0x180000
	s_addc_u32 s15, s13, 0
	s_add_u32 s18, s14, 0x180000
	s_addc_u32 s19, s15, 0
	global_load_dword v20, v0, s[10:11] nt
	global_load_dword v21, v1, s[10:11] nt
	global_load_dword v22, v2, s[10:11] nt
	global_load_dword v23, v3, s[10:11] nt
	global_load_dword v24, v4, s[10:11] nt
	global_load_dword v25, v5, s[10:11] nt
	global_load_dword v26, v6, s[10:11] nt
	global_load_dword v27, v7, s[10:11] nt
	global_load_dword v28, v0, s[12:13] nt
	global_load_dword v29, v1, s[12:13] nt
	global_load_dword v30, v2, s[12:13] nt
	global_load_dword v31, v3, s[12:13] nt
	global_load_dword v32, v4, s[12:13] nt
	global_load_dword v33, v5, s[12:13] nt
	global_load_dword v34, v6, s[12:13] nt
	global_load_dword v35, v7, s[12:13] nt
	global_load_dword v36, v0, s[14:15] nt
	global_load_dword v37, v1, s[14:15] nt
	global_load_dword v38, v2, s[14:15] nt
	global_load_dword v39, v3, s[14:15] nt
	global_load_dword v40, v4, s[14:15] nt
	global_load_dword v41, v5, s[14:15] nt
	global_load_dword v42, v6, s[14:15] nt
	global_load_dword v43, v7, s[14:15] nt
	global_load_dword v44, v0, s[18:19] nt
	global_load_dword v45, v1, s[18:19] nt
	global_load_dword v46, v2, s[18:19] nt
	global_load_dword v47, v3, s[18:19] nt
	global_load_dword v48, v4, s[18:19] nt
	global_load_dword v49, v5, s[18:19] nt
	global_load_dword v50, v6, s[18:19] nt
	global_load_dword v51, v7, s[18:19] nt
	s_waitcnt vmcnt(32)
	ds_write_b32 v8, v52 offset:0
	ds_write_b32 v8, v53 offset:264
	ds_write_b32 v8, v54 offset:528
	ds_write_b32 v8, v55 offset:792
	ds_write_b32 v8, v56 offset:1056
	ds_write_b32 v8, v57 offset:1320
	ds_write_b32 v8, v58 offset:1584
	ds_write_b32 v8, v59 offset:1848
	ds_write_b32 v8, v60 offset:2112
	ds_write_b32 v8, v61 offset:2376
	ds_write_b32 v8, v62 offset:2640
	ds_write_b32 v8, v63 offset:2904
	ds_write_b32 v8, v64 offset:3168
	ds_write_b32 v8, v65 offset:3432
	ds_write_b32 v8, v66 offset:3696
	ds_write_b32 v8, v67 offset:3960
	ds_write_b32 v8, v68 offset:4224
	ds_write_b32 v8, v69 offset:4488
	ds_write_b32 v8, v70 offset:4752
	ds_write_b32 v8, v71 offset:5016
	ds_write_b32 v8, v72 offset:5280
	ds_write_b32 v8, v73 offset:5544
	ds_write_b32 v8, v74 offset:5808
	ds_write_b32 v8, v75 offset:6072
	ds_write_b32 v8, v76 offset:6336
	ds_write_b32 v8, v77 offset:6600
	ds_write_b32 v8, v78 offset:6864
	ds_write_b32 v8, v79 offset:7128
	ds_write_b32 v8, v80 offset:7392
	ds_write_b32 v8, v81 offset:7656
	ds_write_b32 v8, v82 offset:7920
	ds_write_b32 v8, v83 offset:8184
	s_lshr_b32 s37, s36, 8
	s_bfe_u32 s38, s36, 0x40003
	s_lshl_b32 s38, s38, 2
	s_add_i32 s37, s37, s38
	s_and_b32 s37, s37, 63
	s_and_b32 s38, s36, 255
	s_lshl_b32 s37, s37, 6
	s_lshl_b32 s38, s38, 17
	s_add_u32 s37, s37, s38
	s_add_u32 s46, s0, s37
	s_addc_u32 s47, s1, 0
	s_waitcnt lgkmcnt(0)
	ds_read2_b32 v[84:85], v9 offset0:0 offset1:8
	ds_read2_b32 v[86:87], v9 offset0:33 offset1:41
	ds_read2_b32 v[88:89], v9 offset0:66 offset1:74
	ds_read2_b32 v[90:91], v9 offset0:99 offset1:107
	ds_read2_b32 v[92:93], v9 offset0:132 offset1:140
	ds_read2_b32 v[94:95], v9 offset0:165 offset1:173
	ds_read2_b32 v[96:97], v9 offset0:198 offset1:206
	ds_read2_b32 v[98:99], v9 offset0:231 offset1:239
	ds_read2_b32 v[100:101], v9 offset0:16 offset1:24
	ds_read2_b32 v[102:103], v9 offset0:49 offset1:57
	ds_read2_b32 v[104:105], v9 offset0:82 offset1:90
	ds_read2_b32 v[106:107], v9 offset0:115 offset1:123
	ds_read2_b32 v[108:109], v9 offset0:148 offset1:156
	ds_read2_b32 v[110:111], v9 offset0:181 offset1:189
	ds_read2_b32 v[112:113], v9 offset0:214 offset1:222
	ds_read2_b32 v[114:115], v9 offset0:247 offset1:255
	s_waitcnt lgkmcnt(0)
	v_mul_f32_e32 v84, 0x42800000, v84
	v_mul_f32_e32 v85, 0x42800000, v85
	v_mul_f32_e32 v86, 0x42800000, v86
	v_mul_f32_e32 v87, 0x42800000, v87
	v_mul_f32_e32 v88, 0x42800000, v88
	v_mul_f32_e32 v89, 0x42800000, v89
	v_mul_f32_e32 v90, 0x42800000, v90
	v_mul_f32_e32 v91, 0x42800000, v91
	v_mul_f32_e32 v92, 0x42800000, v92
	v_mul_f32_e32 v93, 0x42800000, v93
	v_mul_f32_e32 v94, 0x42800000, v94
	v_mul_f32_e32 v95, 0x42800000, v95
	v_mul_f32_e32 v96, 0x42800000, v96
	v_mul_f32_e32 v97, 0x42800000, v97
	v_mul_f32_e32 v98, 0x42800000, v98
	v_mul_f32_e32 v99, 0x42800000, v99
	v_mul_f32_e32 v100, 0x42800000, v100
	v_mul_f32_e32 v101, 0x42800000, v101
	v_mul_f32_e32 v102, 0x42800000, v102
	v_mul_f32_e32 v103, 0x42800000, v103
	v_mul_f32_e32 v104, 0x42800000, v104
	v_mul_f32_e32 v105, 0x42800000, v105
	v_mul_f32_e32 v106, 0x42800000, v106
	v_mul_f32_e32 v107, 0x42800000, v107
	v_mul_f32_e32 v108, 0x42800000, v108
	v_mul_f32_e32 v109, 0x42800000, v109
	v_mul_f32_e32 v110, 0x42800000, v110
	v_mul_f32_e32 v111, 0x42800000, v111
	v_mul_f32_e32 v112, 0x42800000, v112
	v_mul_f32_e32 v113, 0x42800000, v113
	v_mul_f32_e32 v114, 0x42800000, v114
	v_mul_f32_e32 v115, 0x42800000, v115
	v_cvt_pk_fp8_f32 v116, v84, v86
	v_cvt_pk_fp8_f32 v117, v92, v94
	v_cvt_pk_fp8_f32 v116, v88, v90 op_sel:[0,0,1]
	v_cvt_pk_fp8_f32 v117, v96, v98 op_sel:[0,0,1]
	v_cvt_pk_fp8_f32 v118, v85, v87
	v_cvt_pk_fp8_f32 v119, v93, v95
	v_cvt_pk_fp8_f32 v118, v89, v91 op_sel:[0,0,1]
	v_cvt_pk_fp8_f32 v119, v97, v99 op_sel:[0,0,1]
	v_cvt_pk_fp8_f32 v120, v100, v102
	v_cvt_pk_fp8_f32 v121, v108, v110
	v_cvt_pk_fp8_f32 v120, v104, v106 op_sel:[0,0,1]
	v_cvt_pk_fp8_f32 v121, v112, v114 op_sel:[0,0,1]
	v_cvt_pk_fp8_f32 v122, v101, v103
	v_cvt_pk_fp8_f32 v123, v109, v111
	v_cvt_pk_fp8_f32 v122, v105, v107 op_sel:[0,0,1]
	v_cvt_pk_fp8_f32 v123, v113, v115 op_sel:[0,0,1]
	global_store_dwordx2 v14, v[116:117], s[46:47]
	global_store_dwordx2 v15, v[118:119], s[46:47]
	global_store_dwordx2 v16, v[120:121], s[46:47]
	global_store_dwordx2 v17, v[122:123], s[46:47]
	s_mov_b32 s36, s20
	s_add_i32 s20, s20, s16
	s_branch .Lp0b_loop
.Lp0b_lastA:
	s_waitcnt vmcnt(0)
	ds_write_b32 v8, v20 offset:0
	ds_write_b32 v8, v21 offset:264
	ds_write_b32 v8, v22 offset:528
	ds_write_b32 v8, v23 offset:792
	ds_write_b32 v8, v24 offset:1056
	ds_write_b32 v8, v25 offset:1320
	ds_write_b32 v8, v26 offset:1584
	ds_write_b32 v8, v27 offset:1848
	ds_write_b32 v8, v28 offset:2112
	ds_write_b32 v8, v29 offset:2376
	ds_write_b32 v8, v30 offset:2640
	ds_write_b32 v8, v31 offset:2904
	ds_write_b32 v8, v32 offset:3168
	ds_write_b32 v8, v33 offset:3432
	ds_write_b32 v8, v34 offset:3696
	ds_write_b32 v8, v35 offset:3960
	ds_write_b32 v8, v36 offset:4224
	ds_write_b32 v8, v37 offset:4488
	ds_write_b32 v8, v38 offset:4752
	ds_write_b32 v8, v39 offset:5016
	ds_write_b32 v8, v40 offset:5280
	ds_write_b32 v8, v41 offset:5544
	ds_write_b32 v8, v42 offset:5808
	ds_write_b32 v8, v43 offset:6072
	ds_write_b32 v8, v44 offset:6336
	ds_write_b32 v8, v45 offset:6600
	ds_write_b32 v8, v46 offset:6864
	ds_write_b32 v8, v47 offset:7128
	ds_write_b32 v8, v48 offset:7392
	ds_write_b32 v8, v49 offset:7656
	ds_write_b32 v8, v50 offset:7920
	ds_write_b32 v8, v51 offset:8184
	s_lshr_b32 s37, s36, 8
	s_bfe_u32 s38, s36, 0x40003
	s_lshl_b32 s38, s38, 2
	s_add_i32 s37, s37, s38
	s_and_b32 s37, s37, 63
	s_and_b32 s38, s36, 255
	s_lshl_b32 s37, s37, 6
	s_lshl_b32 s38, s38, 17
	s_add_u32 s37, s37, s38
	s_add_u32 s46, s0, s37
	s_addc_u32 s47, s1, 0
	s_waitcnt lgkmcnt(0)
	ds_read2_b32 v[84:85], v9 offset0:0 offset1:8
	ds_read2_b32 v[86:87], v9 offset0:33 offset1:41
	ds_read2_b32 v[88:89], v9 offset0:66 offset1:74
	ds_read2_b32 v[90:91], v9 offset0:99 offset1:107
	ds_read2_b32 v[92:93], v9 offset0:132 offset1:140
	ds_read2_b32 v[94:95], v9 offset0:165 offset1:173
	ds_read2_b32 v[96:97], v9 offset0:198 offset1:206
	ds_read2_b32 v[98:99], v9 offset0:231 offset1:239
	ds_read2_b32 v[100:101], v9 offset0:16 offset1:24
	ds_read2_b32 v[102:103], v9 offset0:49 offset1:57
	ds_read2_b32 v[104:105], v9 offset0:82 offset1:90
	ds_read2_b32 v[106:107], v9 offset0:115 offset1:123
	ds_read2_b32 v[108:109], v9 offset0:148 offset1:156
	ds_read2_b32 v[110:111], v9 offset0:181 offset1:189
	ds_read2_b32 v[112:113], v9 offset0:214 offset1:222
	ds_read2_b32 v[114:115], v9 offset0:247 offset1:255
	s_waitcnt lgkmcnt(0)
	v_mul_f32_e32 v84, 0x42800000, v84
	v_mul_f32_e32 v85, 0x42800000, v85
	v_mul_f32_e32 v86, 0x42800000, v86
	v_mul_f32_e32 v87, 0x42800000, v87
	v_mul_f32_e32 v88, 0x42800000, v88
	v_mul_f32_e32 v89, 0x42800000, v89
	v_mul_f32_e32 v90, 0x42800000, v90
	v_mul_f32_e32 v91, 0x42800000, v91
	v_mul_f32_e32 v92, 0x42800000, v92
	v_mul_f32_e32 v93, 0x42800000, v93
	v_mul_f32_e32 v94, 0x42800000, v94
	v_mul_f32_e32 v95, 0x42800000, v95
	v_mul_f32_e32 v96, 0x42800000, v96
	v_mul_f32_e32 v97, 0x42800000, v97
	v_mul_f32_e32 v98, 0x42800000, v98
	v_mul_f32_e32 v99, 0x42800000, v99
	v_mul_f32_e32 v100, 0x42800000, v100
	v_mul_f32_e32 v101, 0x42800000, v101
	v_mul_f32_e32 v102, 0x42800000, v102
	v_mul_f32_e32 v103, 0x42800000, v103
	v_mul_f32_e32 v104, 0x42800000, v104
	v_mul_f32_e32 v105, 0x42800000, v105
	v_mul_f32_e32 v106, 0x42800000, v106
	v_mul_f32_e32 v107, 0x42800000, v107
	v_mul_f32_e32 v108, 0x42800000, v108
	v_mul_f32_e32 v109, 0x42800000, v109
	v_mul_f32_e32 v110, 0x42800000, v110
	v_mul_f32_e32 v111, 0x42800000, v111
	v_mul_f32_e32 v112, 0x42800000, v112
	v_mul_f32_e32 v113, 0x42800000, v113
	v_mul_f32_e32 v114, 0x42800000, v114
	v_mul_f32_e32 v115, 0x42800000, v115
	v_cvt_pk_fp8_f32 v116, v84, v86
	v_cvt_pk_fp8_f32 v117, v92, v94
	v_cvt_pk_fp8_f32 v116, v88, v90 op_sel:[0,0,1]
	v_cvt_pk_fp8_f32 v117, v96, v98 op_sel:[0,0,1]
	v_cvt_pk_fp8_f32 v118, v85, v87
	v_cvt_pk_fp8_f32 v119, v93, v95
	v_cvt_pk_fp8_f32 v118, v89, v91 op_sel:[0,0,1]
	v_cvt_pk_fp8_f32 v119, v97, v99 op_sel:[0,0,1]
	v_cvt_pk_fp8_f32 v120, v100, v102
	v_cvt_pk_fp8_f32 v121, v108, v110
	v_cvt_pk_fp8_f32 v120, v104, v106 op_sel:[0,0,1]
	v_cvt_pk_fp8_f32 v121, v112, v114 op_sel:[0,0,1]
	v_cvt_pk_fp8_f32 v122, v101, v103
	v_cvt_pk_fp8_f32 v123, v109, v111
	v_cvt_pk_fp8_f32 v122, v105, v107 op_sel:[0,0,1]
	v_cvt_pk_fp8_f32 v123, v113, v115 op_sel:[0,0,1]
	global_store_dwordx2 v14, v[116:117], s[46:47]
	global_store_dwordx2 v15, v[118:119], s[46:47]
	global_store_dwordx2 v16, v[120:121], s[46:47]
	global_store_dwordx2 v17, v[122:123], s[46:47]
	s_branch .Lp0b_done
.Lp0b_lastB:
	s_waitcnt vmcnt(0)
	ds_write_b32 v8, v52 offset:0
	ds_write_b32 v8, v53 offset:264
	ds_write_b32 v8, v54 offset:528
	ds_write_b32 v8, v55 offset:792
	ds_write_b32 v8, v56 offset:1056
	ds_write_b32 v8, v57 offset:1320
	ds_write_b32 v8, v58 offset:1584
	ds_write_b32 v8, v59 offset:1848
	ds_write_b32 v8, v60 offset:2112
	ds_write_b32 v8, v61 offset:2376
	ds_write_b32 v8, v62 offset:2640
	ds_write_b32 v8, v63 offset:2904
	ds_write_b32 v8, v64 offset:3168
	ds_write_b32 v8, v65 offset:3432
	ds_write_b32 v8, v66 offset:3696
	ds_write_b32 v8, v67 offset:3960
	ds_write_b32 v8, v68 offset:4224
	ds_write_b32 v8, v69 offset:4488
	ds_write_b32 v8, v70 offset:4752
	ds_write_b32 v8, v71 offset:5016
	ds_write_b32 v8, v72 offset:5280
	ds_write_b32 v8, v73 offset:5544
	ds_write_b32 v8, v74 offset:5808
	ds_write_b32 v8, v75 offset:6072
	ds_write_b32 v8, v76 offset:6336
	ds_write_b32 v8, v77 offset:6600
	ds_write_b32 v8, v78 offset:6864
	ds_write_b32 v8, v79 offset:7128
	ds_write_b32 v8, v80 offset:7392
	ds_write_b32 v8, v81 offset:7656
	ds_write_b32 v8, v82 offset:7920
	ds_write_b32 v8, v83 offset:8184
	s_lshr_b32 s37, s36, 8
	s_bfe_u32 s38, s36, 0x40003
	s_lshl_b32 s38, s38, 2
	s_add_i32 s37, s37, s38
	s_and_b32 s37, s37, 63
	s_and_b32 s38, s36, 255
	s_lshl_b32 s37, s37, 6
	s_lshl_b32 s38, s38, 17
	s_add_u32 s37, s37, s38
	s_add_u32 s46, s0, s37
	s_addc_u32 s47, s1, 0
	s_waitcnt lgkmcnt(0)
	ds_read2_b32 v[84:85], v9 offset0:0 offset1:8
	ds_read2_b32 v[86:87], v9 offset0:33 offset1:41
	ds_read2_b32 v[88:89], v9 offset0:66 offset1:74
	ds_read2_b32 v[90:91], v9 offset0:99 offset1:107
	ds_read2_b32 v[92:93], v9 offset0:132 offset1:140
	ds_read2_b32 v[94:95], v9 offset0:165 offset1:173
	ds_read2_b32 v[96:97], v9 offset0:198 offset1:206
	ds_read2_b32 v[98:99], v9 offset0:231 offset1:239
	ds_read2_b32 v[100:101], v9 offset0:16 offset1:24
	ds_read2_b32 v[102:103], v9 offset0:49 offset1:57
	ds_read2_b32 v[104:105], v9 offset0:82 offset1:90
	ds_read2_b32 v[106:107], v9 offset0:115 offset1:123
	ds_read2_b32 v[108:109], v9 offset0:148 offset1:156
	ds_read2_b32 v[110:111], v9 offset0:181 offset1:189
	ds_read2_b32 v[112:113], v9 offset0:214 offset1:222
	ds_read2_b32 v[114:115], v9 offset0:247 offset1:255
	s_waitcnt lgkmcnt(0)
	v_mul_f32_e32 v84, 0x42800000, v84
	v_mul_f32_e32 v85, 0x42800000, v85
	v_mul_f32_e32 v86, 0x42800000, v86
	v_mul_f32_e32 v87, 0x42800000, v87
	v_mul_f32_e32 v88, 0x42800000, v88
	v_mul_f32_e32 v89, 0x42800000, v89
	v_mul_f32_e32 v90, 0x42800000, v90
	v_mul_f32_e32 v91, 0x42800000, v91
	v_mul_f32_e32 v92, 0x42800000, v92
	v_mul_f32_e32 v93, 0x42800000, v93
	v_mul_f32_e32 v94, 0x42800000, v94
	v_mul_f32_e32 v95, 0x42800000, v95
	v_mul_f32_e32 v96, 0x42800000, v96
	v_mul_f32_e32 v97, 0x42800000, v97
	v_mul_f32_e32 v98, 0x42800000, v98
	v_mul_f32_e32 v99, 0x42800000, v99
	v_mul_f32_e32 v100, 0x42800000, v100
	v_mul_f32_e32 v101, 0x42800000, v101
	v_mul_f32_e32 v102, 0x42800000, v102
	v_mul_f32_e32 v103, 0x42800000, v103
	v_mul_f32_e32 v104, 0x42800000, v104
	v_mul_f32_e32 v105, 0x42800000, v105
	v_mul_f32_e32 v106, 0x42800000, v106
	v_mul_f32_e32 v107, 0x42800000, v107
	v_mul_f32_e32 v108, 0x42800000, v108
	v_mul_f32_e32 v109, 0x42800000, v109
	v_mul_f32_e32 v110, 0x42800000, v110
	v_mul_f32_e32 v111, 0x42800000, v111
	v_mul_f32_e32 v112, 0x42800000, v112
	v_mul_f32_e32 v113, 0x42800000, v113
	v_mul_f32_e32 v114, 0x42800000, v114
	v_mul_f32_e32 v115, 0x42800000, v115
	v_cvt_pk_fp8_f32 v116, v84, v86
	v_cvt_pk_fp8_f32 v117, v92, v94
	v_cvt_pk_fp8_f32 v116, v88, v90 op_sel:[0,0,1]
	v_cvt_pk_fp8_f32 v117, v96, v98 op_sel:[0,0,1]
	v_cvt_pk_fp8_f32 v118, v85, v87
	v_cvt_pk_fp8_f32 v119, v93, v95
	v_cvt_pk_fp8_f32 v118, v89, v91 op_sel:[0,0,1]
	v_cvt_pk_fp8_f32 v119, v97, v99 op_sel:[0,0,1]
	v_cvt_pk_fp8_f32 v120, v100, v102
	v_cvt_pk_fp8_f32 v121, v108, v110
	v_cvt_pk_fp8_f32 v120, v104, v106 op_sel:[0,0,1]
	v_cvt_pk_fp8_f32 v121, v112, v114 op_sel:[0,0,1]
	v_cvt_pk_fp8_f32 v122, v101, v103
	v_cvt_pk_fp8_f32 v123, v109, v111
	v_cvt_pk_fp8_f32 v122, v105, v107 op_sel:[0,0,1]
	v_cvt_pk_fp8_f32 v123, v113, v115 op_sel:[0,0,1]
	global_store_dwordx2 v14, v[116:117], s[46:47]
	global_store_dwordx2 v15, v[118:119], s[46:47]
	global_store_dwordx2 v16, v[120:121], s[46:47]
	global_store_dwordx2 v17, v[122:123], s[46:47]
